# grid barriers 1-11: arrival protocol hand-written on the scalar unit (generation = barriers passed, no integer divisions, short spin loop); unused generation words no longer bumped
# speedup vs baseline: 1.0421x; 1.0027x over previous
_Z14fwd_megakernel3Ctx:
	s_load_dwordx8 s[24:31], s[0:1], 0xa0
	s_load_dwordx8 s[8:15], s[0:1], 0x80
	s_load_dword s3, s[0:1], 0xc0
	s_add_u32 s6, s0, 0xb8
	s_addc_u32 s7, s1, 0
	v_and_b32_e32 v230, 0x3ff, v0
	v_cmp_eq_u32_e64 s[16:17], 0, v230
	s_waitcnt lgkmcnt(0)
	v_writelane_b32 v255, s3, 0
	s_mov_b64 s[4:5], exec
	v_writelane_b32 v255, s16, 1
	s_nop 1
	v_writelane_b32 v255, s17, 2
	s_mov_b32 s22, 1
	s_nop 0
	v_writelane_b32 v255, s22, 12
	s_and_b64 s[16:17], s[4:5], s[16:17]
	s_mov_b64 exec, s[16:17]
	s_cbranch_execz .LBB0_2
	s_add_i32 s3, 0, 0x23ff0
	v_mov_b32_e32 v1, 0
	v_mov_b32_e32 v2, s3
	s_add_i32 s3, 0, 0x23ff4
	ds_write_b32 v2, v1
	v_mov_b32_e32 v2, s3
	ds_write_b32 v2, v1

.LBB0_254:
	s_or_b64 exec, exec, s[20:21]
	buffer_inv sc1
	v_cvt_f32_u32_e32 v3, v0
	s_waitcnt vmcnt(0)
	v_readfirstlane_b32 s3, v2
	s_add_u32 s20, s28, 0x67500
	s_addc_u32 s21, s29, 0
	v_rcp_iflag_f32_e32 v3, v3
	v_add_u32_e32 v1, s3, v1
	v_add_u32_e32 v4, 1, v1
	s_mov_b64 s[46:47], 0
	v_mul_f32_e32 v2, 0x4f7ffffe, v3
	v_cvt_u32_f32_e32 v2, v2
	v_sub_u32_e32 v3, 0, v0
	v_mul_lo_u32 v3, v3, v2
	v_mul_hi_u32 v3, v2, v3
	v_add_u32_e32 v2, v2, v3
	v_mul_hi_u32 v2, v1, v2
	v_mul_lo_u32 v3, v2, v0
	v_sub_u32_e32 v1, v1, v3
	v_add_u32_e32 v5, 1, v2
	v_cmp_ge_u32_e32 vcc, v1, v0
	v_sub_u32_e32 v3, v1, v0
	s_nop 0
	v_cndmask_b32_e32 v2, v2, v5, vcc
	v_cndmask_b32_e32 v1, v1, v3, vcc
	v_add_u32_e32 v3, 1, v2
	v_cmp_ge_u32_e32 vcc, v1, v0
	s_nop 1
	v_cndmask_b32_e32 v2, v2, v3, vcc
	v_mul_lo_u32 v1, v0, v2
	v_add_u32_e32 v0, v1, v0
	v_cmp_ne_u32_e32 vcc, v4, v0
	v_mov_b32_e32 v5, v0
	v_mov_b64_e32 v[0:1], s[20:21]
	s_and_saveexec_b64 s[6:7], vcc
	s_cbranch_execz .LBB0_266
	v_mov_b32_e32 v0, 0
	global_load_dword v1, v0, s[20:21] offset:-256 sc1
	s_mov_b64 s[50:51], 0
	s_waitcnt vmcnt(0)
	v_cmp_lt_u32_e32 vcc, v1, v5
	s_and_saveexec_b64 s[48:49], vcc
	s_cbranch_execz .LBB0_265
	s_add_u32 s46, s28, 0x64200
	s_addc_u32 s47, s29, 0
	s_mov_b32 s3, 1
	s_branch .LBB0_258

.LBB0_268:
	s_or_b64 exec, exec, s[6:7]
	s_mov_b64 s[6:7], exec
	v_mbcnt_lo_u32_b32 v0, s6, 0
	v_mbcnt_hi_u32_b32 v0, s7, v0
	v_cmp_eq_u32_e32 vcc, 0, v0
	s_waitcnt vmcnt(0)
	s_and_saveexec_b64 s[20:21], vcc
	s_cbranch_execz .LBB0_270
	s_bcnt1_i32_b64 s3, s[6:7]
	v_mov_b32_e32 v0, 0x2000
	v_mov_b32_e32 v1, s3
.LBB0_270:
	s_or_b64 exec, exec, s[20:21]
	s_waitcnt vmcnt(0)

.LBB0_346:
	s_getreg_b32 s3, hwreg(HW_REG_XCC_ID, 0, 4)
	s_waitcnt vmcnt(0)
	s_waitcnt vmcnt(0)
	s_barrier
	s_mov_b64 s[0:1], exec
	v_readlane_b32 s4, v255, 1
	v_readlane_b32 s5, v255, 2
	s_and_b64 s[4:5], s[0:1], s[4:5]
	s_mov_b64 exec, s[4:5]
	s_cbranch_execz .LBB0_400
	s_waitcnt vmcnt(0) lgkmcnt(0)
	s_and_b32 s3, s3, 15
	s_lshl_b32 s3, s3, 8
	s_add_u32 s6, s28, 0x65400
	s_addc_u32 s7, s29, 0
	s_add_u32 s6, s6, s3
	s_addc_u32 s7, s7, 0
	v_mov_b32_e32 v0, 0
	v_mov_b32_e32 v1, 1
	global_atomic_add v2, v0, v1, s[6:7] sc0
	v_mov_b32_e32 v3, 0x23ff0
	ds_read_b64 v[4:5], v3
	v_readlane_b32 s10, v255, 12
	s_add_u32 s8, s28, 0x67400
	s_addc_u32 s9, s29, 0
	s_add_i32 s10, s10, 1
	s_nop 0
	v_writelane_b32 v255, s10, 12
	s_waitcnt lgkmcnt(0)
	v_readfirstlane_b32 s12, v4
	v_readfirstlane_b32 s11, v5
	s_mul_i32 s11, s11, s10
	s_mul_i32 s10, s12, s10
	s_waitcnt vmcnt(0)
	v_readfirstlane_b32 s12, v2
	s_add_i32 s12, s12, 1
	s_cmp_lg_u32 s12, s10
	s_cbranch_scc1 .Lhb1_wait
	buffer_wbl2 sc1
	s_waitcnt vmcnt(0)
	global_atomic_add v2, v0, v1, s[8:9] sc0
	buffer_inv sc1
	s_waitcnt vmcnt(0)
	v_readfirstlane_b32 s12, v2
	s_add_i32 s12, s12, 1
	s_cmp_eq_u32 s12, s11
	s_cbranch_scc1 .Lhb1_done
	s_branch .Lhb1_poll

.Lhb1_poll:
	s_mov_b32 s13, 0
.Lhb1_loop:
	global_load_dword v2, v0, s[8:9] sc1
	s_waitcnt vmcnt(0)
	v_readfirstlane_b32 s12, v2
	s_cmp_ge_u32 s12, s11
	s_cbranch_scc1 .Lhb1_done
	s_sleep 1
	s_add_i32 s13, s13, 1
	s_and_b32 s12, s13, 0xff
	s_cmp_lg_u32 s12, 0
	s_cbranch_scc1 .Lhb1_loop
	s_add_u32 s6, s28, 0x64200
	s_addc_u32 s7, s29, 0
	global_load_dword v2, v0, s[6:7] sc1
	s_waitcnt vmcnt(0)
	v_readfirstlane_b32 s12, v2
	s_cmp_lg_u32 s12, 0
	s_cbranch_scc1 .Lhb1_done
	s_cmp_le_u32 s13, 0x40000
	s_cbranch_scc1 .Lhb1_loop
	global_atomic_add v0, v1, s[6:7]
.Lhb1_done:
	s_waitcnt vmcnt(0)
	s_branch .LBB0_400

.LBB0_392:
	s_add_u32 s6, s26, 0x2000000
	s_addc_u32 s7, s27, 0
	s_add_i32 s55, s17, 0xffffff50
	s_movk_i32 s18, 0x400
	s_movk_i32 s19, 0xb00
	s_mov_b32 s48, 2
	s_cbranch_execz .LBB0_296
	s_branch .LBB0_297
.LBB0_400:
	s_or_b64 exec, exec, s[0:1]
	s_waitcnt lgkmcnt(0)
	v_mov_b32_e32 v0, v230
	s_cmpk_lt_i32 s2, 0x100
	s_barrier
	s_cselect_b64 s[0:1], -1, 0
	s_cmpk_gt_i32 s2, 0xff
	v_readfirstlane_b32 s6, v0
	s_cbranch_scc1 .LBB0_406
	s_ashr_i32 s3, s2, 31
	s_lshr_b32 s3, s3, 29
	s_add_i32 s3, s2, s3
	s_and_b32 s4, s3, -8
	s_sub_i32 s7, s2, s4
	s_cmp_gt_i32 s7, -1
	s_cbranch_scc0 .LBB0_403
	s_lshl_b32 s8, s7, 5
	s_cbranch_execz .LBB0_404
	s_branch .LBB0_405

.LBB0_462:
	s_getreg_b32 s3, hwreg(HW_REG_XCC_ID, 0, 4)
	s_waitcnt vmcnt(0)
	s_waitcnt vmcnt(0) lgkmcnt(0)
	s_barrier
	s_mov_b64 s[0:1], exec
	v_readlane_b32 s4, v255, 1
	v_readlane_b32 s5, v255, 2
	s_and_b64 s[4:5], s[0:1], s[4:5]
	s_mov_b64 exec, s[4:5]
	s_cbranch_execz .LBB0_514
	s_waitcnt vmcnt(0) lgkmcnt(0)
	s_and_b32 s3, s3, 15
	s_lshl_b32 s3, s3, 8
	s_add_u32 s6, s28, 0x65400
	s_addc_u32 s7, s29, 0
	s_add_u32 s6, s6, s3
	s_addc_u32 s7, s7, 0
	v_mov_b32_e32 v0, 0
	v_mov_b32_e32 v1, 1
	global_atomic_add v2, v0, v1, s[6:7] sc0
	v_mov_b32_e32 v3, 0x23ff0
	ds_read_b64 v[4:5], v3
	v_readlane_b32 s10, v255, 12
	s_add_u32 s8, s28, 0x67400
	s_addc_u32 s9, s29, 0
	s_add_i32 s10, s10, 1
	s_nop 0
	v_writelane_b32 v255, s10, 12
	s_waitcnt lgkmcnt(0)
	v_readfirstlane_b32 s12, v4
	v_readfirstlane_b32 s11, v5
	s_mul_i32 s11, s11, s10
	s_mul_i32 s10, s12, s10
	s_waitcnt vmcnt(0)
	v_readfirstlane_b32 s12, v2
	s_add_i32 s12, s12, 1
	s_cmp_lg_u32 s12, s10
	s_cbranch_scc1 .Lhb2_wait
	buffer_wbl2 sc1
	s_waitcnt vmcnt(0)
	global_atomic_add v2, v0, v1, s[8:9] sc0
	buffer_inv sc1
	s_waitcnt vmcnt(0)
	v_readfirstlane_b32 s12, v2
	s_add_i32 s12, s12, 1
	s_cmp_eq_u32 s12, s11
	s_cbranch_scc1 .Lhb2_done
	s_branch .Lhb2_poll

.LBB0_642:
	s_getreg_b32 s3, hwreg(HW_REG_XCC_ID, 0, 4)
	s_waitcnt vmcnt(0)
	s_waitcnt lgkmcnt(0)
	s_barrier
	s_mov_b64 s[0:1], exec
	v_readlane_b32 s4, v255, 1
	v_readlane_b32 s5, v255, 2
	s_and_b64 s[4:5], s[0:1], s[4:5]
	s_mov_b64 exec, s[4:5]
	s_cbranch_execz .LBB0_694
	s_waitcnt vmcnt(0) lgkmcnt(0)
	s_and_b32 s3, s3, 15
	s_lshl_b32 s3, s3, 8
	s_add_u32 s6, s28, 0x65400
	s_addc_u32 s7, s29, 0
	s_add_u32 s6, s6, s3
	s_addc_u32 s7, s7, 0
	v_mov_b32_e32 v0, 0
	v_mov_b32_e32 v1, 1
	global_atomic_add v2, v0, v1, s[6:7] sc0
	v_mov_b32_e32 v3, 0x23ff0
	ds_read_b64 v[4:5], v3
	v_readlane_b32 s10, v255, 12
	s_add_u32 s8, s28, 0x67400
	s_addc_u32 s9, s29, 0
	s_add_i32 s10, s10, 1
	s_nop 0
	v_writelane_b32 v255, s10, 12
	s_waitcnt lgkmcnt(0)
	v_readfirstlane_b32 s12, v4
	v_readfirstlane_b32 s11, v5
	s_mul_i32 s11, s11, s10
	s_mul_i32 s10, s12, s10
	s_waitcnt vmcnt(0)
	v_readfirstlane_b32 s12, v2
	s_add_i32 s12, s12, 1
	s_cmp_lg_u32 s12, s10
	s_cbranch_scc1 .Lhb3_wait
	buffer_wbl2 sc1
	s_waitcnt vmcnt(0)
	global_atomic_add v2, v0, v1, s[8:9] sc0
	buffer_inv sc1
	s_waitcnt vmcnt(0)
	v_readfirstlane_b32 s12, v2
	s_add_i32 s12, s12, 1
	s_cmp_eq_u32 s12, s11
	s_cbranch_scc1 .Lhb3_done
	s_branch .Lhb3_poll

.LBB0_697:
	s_getreg_b32 s3, hwreg(HW_REG_XCC_ID, 0, 4)
	s_waitcnt vmcnt(0)
	s_barrier
	s_mov_b64 s[0:1], exec
	v_readlane_b32 s4, v255, 1
	v_readlane_b32 s5, v255, 2
	s_and_b64 s[4:5], s[0:1], s[4:5]
	s_mov_b64 exec, s[4:5]
	s_cbranch_execz .LBB0_749
	s_waitcnt vmcnt(0) lgkmcnt(0)
	s_and_b32 s3, s3, 15
	s_lshl_b32 s3, s3, 8
	s_add_u32 s6, s28, 0x65400
	s_addc_u32 s7, s29, 0
	s_add_u32 s6, s6, s3
	s_addc_u32 s7, s7, 0
	v_mov_b32_e32 v0, 0
	v_mov_b32_e32 v1, 1
	global_atomic_add v2, v0, v1, s[6:7] sc0
	v_mov_b32_e32 v3, 0x23ff0
	ds_read_b64 v[4:5], v3
	v_readlane_b32 s10, v255, 12
	s_add_u32 s8, s28, 0x67400
	s_addc_u32 s9, s29, 0
	s_add_i32 s10, s10, 1
	s_nop 0
	v_writelane_b32 v255, s10, 12
	s_waitcnt lgkmcnt(0)
	v_readfirstlane_b32 s12, v4
	v_readfirstlane_b32 s11, v5
	s_mul_i32 s11, s11, s10
	s_mul_i32 s10, s12, s10
	s_waitcnt vmcnt(0)
	v_readfirstlane_b32 s12, v2
	s_add_i32 s12, s12, 1
	s_cmp_lg_u32 s12, s10
	s_cbranch_scc1 .Lhb4_wait
	buffer_wbl2 sc1
	s_waitcnt vmcnt(0)
	global_atomic_add v2, v0, v1, s[8:9] sc0
	buffer_inv sc1
	s_waitcnt vmcnt(0)
	v_readfirstlane_b32 s12, v2
	s_add_i32 s12, s12, 1
	s_cmp_eq_u32 s12, s11
	s_cbranch_scc1 .Lhb4_done
	s_branch .Lhb4_poll

.LBB0_968:
	s_getreg_b32 s3, hwreg(HW_REG_XCC_ID, 0, 4)
	s_waitcnt vmcnt(0)
	s_barrier
	s_mov_b64 s[0:1], exec
	v_readlane_b32 s6, v255, 1
	v_readlane_b32 s7, v255, 2
	s_and_b64 s[6:7], s[0:1], s[6:7]
	s_mov_b64 exec, s[6:7]
	s_cbranch_execz .LBB0_1020
	s_waitcnt vmcnt(0) lgkmcnt(0)
	s_and_b32 s3, s3, 15
	s_lshl_b32 s3, s3, 8
	s_add_u32 s6, s28, 0x65400
	s_addc_u32 s7, s29, 0
	s_add_u32 s6, s6, s3
	s_addc_u32 s7, s7, 0
	v_mov_b32_e32 v0, 0
	v_mov_b32_e32 v1, 1
	global_atomic_add v2, v0, v1, s[6:7] sc0
	v_mov_b32_e32 v3, 0x23ff0
	ds_read_b64 v[4:5], v3
	v_readlane_b32 s10, v255, 12
	s_add_u32 s8, s28, 0x67400
	s_addc_u32 s9, s29, 0
	s_add_i32 s10, s10, 1
	s_nop 0
	v_writelane_b32 v255, s10, 12
	s_waitcnt lgkmcnt(0)
	v_readfirstlane_b32 s12, v4
	v_readfirstlane_b32 s11, v5
	s_mul_i32 s11, s11, s10
	s_mul_i32 s10, s12, s10
	s_waitcnt vmcnt(0)
	v_readfirstlane_b32 s12, v2
	s_add_i32 s12, s12, 1
	s_cmp_lg_u32 s12, s10
	s_cbranch_scc1 .Lhb6_wait
	buffer_wbl2 sc1
	s_waitcnt vmcnt(0)
	global_atomic_add v2, v0, v1, s[8:9] sc0
	buffer_inv sc1
	s_waitcnt vmcnt(0)
	v_readfirstlane_b32 s12, v2
	s_add_i32 s12, s12, 1
	s_cmp_eq_u32 s12, s11
	s_cbranch_scc1 .Lhb6_done
	s_branch .Lhb6_poll

.LBB0_1023:
	s_or_b64 exec, exec, s[6:7]
	s_getreg_b32 s3, hwreg(HW_REG_XCC_ID, 0, 4)
	s_waitcnt vmcnt(0)
	s_barrier
	s_mov_b64 s[0:1], exec
	v_readlane_b32 s6, v255, 1
	v_readlane_b32 s7, v255, 2
	s_and_b64 s[6:7], s[0:1], s[6:7]
	s_mov_b64 exec, s[6:7]
	s_cbranch_execz .LBB0_1075
	s_waitcnt vmcnt(0) lgkmcnt(0)
	s_and_b32 s3, s3, 15
	s_lshl_b32 s3, s3, 8
	s_add_u32 s6, s28, 0x65400
	s_addc_u32 s7, s29, 0
	s_add_u32 s6, s6, s3
	s_addc_u32 s7, s7, 0
	v_mov_b32_e32 v0, 0
	v_mov_b32_e32 v1, 1
	global_atomic_add v2, v0, v1, s[6:7] sc0
	v_mov_b32_e32 v3, 0x23ff0
	ds_read_b64 v[4:5], v3
	v_readlane_b32 s10, v255, 12
	s_add_u32 s8, s28, 0x67400
	s_addc_u32 s9, s29, 0
	s_add_i32 s10, s10, 1
	s_nop 0
	v_writelane_b32 v255, s10, 12
	s_waitcnt lgkmcnt(0)
	v_readfirstlane_b32 s12, v4
	v_readfirstlane_b32 s11, v5
	s_mul_i32 s11, s11, s10
	s_mul_i32 s10, s12, s10
	s_waitcnt vmcnt(0)
	v_readfirstlane_b32 s12, v2
	s_add_i32 s12, s12, 1
	s_cmp_lg_u32 s12, s10
	s_cbranch_scc1 .Lhb7_wait
	buffer_wbl2 sc1
	s_waitcnt vmcnt(0)
	global_atomic_add v2, v0, v1, s[8:9] sc0
	buffer_inv sc1
	s_waitcnt vmcnt(0)
	v_readfirstlane_b32 s12, v2
	s_add_i32 s12, s12, 1
	s_cmp_eq_u32 s12, s11
	s_cbranch_scc1 .Lhb7_done
	s_branch .Lhb7_poll

.LBB0_1276:
	s_getreg_b32 s3, hwreg(HW_REG_XCC_ID, 0, 4)
	s_waitcnt vmcnt(0)
	s_waitcnt vmcnt(0) lgkmcnt(0)
	s_barrier
	s_mov_b64 s[4:5], exec
	v_readlane_b32 s6, v255, 1
	v_readlane_b32 s7, v255, 2
	s_and_b64 s[6:7], s[4:5], s[6:7]
	s_mov_b64 exec, s[6:7]
	s_cbranch_execz .LBB0_1328
	s_waitcnt vmcnt(0) lgkmcnt(0)
	s_and_b32 s3, s3, 15
	s_lshl_b32 s3, s3, 8
	s_add_u32 s6, s28, 0x65400
	s_addc_u32 s7, s29, 0
	s_add_u32 s6, s6, s3
	s_addc_u32 s7, s7, 0
	v_mov_b32_e32 v0, 0
	v_mov_b32_e32 v1, 1
	global_atomic_add v2, v0, v1, s[6:7] sc0
	v_mov_b32_e32 v3, 0x23ff0
	ds_read_b64 v[4:5], v3
	v_readlane_b32 s10, v255, 12
	s_add_u32 s8, s28, 0x67400
	s_addc_u32 s9, s29, 0
	s_add_i32 s10, s10, 1
	s_nop 0
	v_writelane_b32 v255, s10, 12
	s_waitcnt lgkmcnt(0)
	v_readfirstlane_b32 s12, v4
	v_readfirstlane_b32 s11, v5
	s_mul_i32 s11, s11, s10
	s_mul_i32 s10, s12, s10
	s_waitcnt vmcnt(0)
	v_readfirstlane_b32 s12, v2
	s_add_i32 s12, s12, 1
	s_cmp_lg_u32 s12, s10
	s_cbranch_scc1 .Lhb10_wait
	buffer_wbl2 sc1
	s_waitcnt vmcnt(0)
	global_atomic_add v2, v0, v1, s[8:9] sc0
	buffer_inv sc1
	s_waitcnt vmcnt(0)
	v_readfirstlane_b32 s12, v2
	s_add_i32 s12, s12, 1
	s_cmp_eq_u32 s12, s11
	s_cbranch_scc1 .Lhb10_done
	s_branch .Lhb10_poll
